# p0 transpose_item: LN column sums straight-line (all lg/lb loads in flight) instead of 128 serialized loads per item
# speedup vs baseline: 1.0126x; 1.0126x over previous
; __device__ __forceinline__ unsigned f2bf(float f) { unsigned u = __builtin_bit_cast(unsigned, f); return (u + 0x7fffu + ((u >> 16) & 1u)) >> 16; }
; __device__ __forceinline__ void transpose_item(const float* W, int K, int nblk, int ldn, bf16* WT, int mode, LAS float* scr, int item, int lane, const float* lg = nullptr, const float* lb = nullptr, float* pcs = nullptr, float* pcb = nullptr) {
;     ...
;     if (lg) { const int n = lane & 31; float acc = 0.f;
; #pragma unroll 8
;         for (int kk = 0; kk < 64; ++kk) { const float w = scr[kk * 33 + n]; const float gk = lg[k0 + kk], bk = lb[k0 + kk]; acc += (lane < 32) ? __uint_as_float(f2bf(w * gk) << 16) : w * bk; }
;         ((lane < 32) ? pcs : pcb)[(size_t)kb * PSTR + r0 + n] = acc; }
.LBB0_23:
	v_mov_b32_e32 v110, s49
	v_mov_b32_e32 v111, s50
	v_mov_b32_e32 v112, s51
	v_mov_b32_e32 v113, s66
	v_mov_b32_e32 v114, v15
	v_mov_b32_e32 v115, 0
	v_cndmask_b32_e64 v110, v110, v112, s[6:7]
	v_cndmask_b32_e64 v111, v111, v113, s[6:7]
	v_lshl_add_u64 v[110:111], v[110:111], 0, v[114:115]
	global_load_dwordx4 v[116:119], v[110:111], off
	global_load_dwordx4 v[120:123], v[110:111], off offset:16
	global_load_dwordx4 v[124:127], v[110:111], off offset:32
	global_load_dwordx4 v[128:131], v[110:111], off offset:48
	global_load_dwordx4 v[132:135], v[110:111], off offset:64
	global_load_dwordx4 v[136:139], v[110:111], off offset:80
	global_load_dwordx4 v[140:143], v[110:111], off offset:96
	global_load_dwordx4 v[144:147], v[110:111], off offset:112
	global_load_dwordx4 v[148:151], v[110:111], off offset:128
	global_load_dwordx4 v[152:155], v[110:111], off offset:144
	global_load_dwordx4 v[156:159], v[110:111], off offset:160
	global_load_dwordx4 v[160:163], v[110:111], off offset:176
	global_load_dwordx4 v[164:167], v[110:111], off offset:192
	global_load_dwordx4 v[168:171], v[110:111], off offset:208
	global_load_dwordx4 v[172:175], v[110:111], off offset:224
	global_load_dwordx4 v[176:179], v[110:111], off offset:240
	ds_read_b32 v180, v3
	ds_read_b32 v181, v3 offset:132
	ds_read_b32 v182, v3 offset:264
	ds_read_b32 v183, v3 offset:396
	ds_read_b32 v184, v3 offset:528
	ds_read_b32 v185, v3 offset:660
	ds_read_b32 v186, v3 offset:792
	ds_read_b32 v187, v3 offset:924
	ds_read_b32 v188, v3 offset:1056
	ds_read_b32 v189, v3 offset:1188
	ds_read_b32 v190, v3 offset:1320
	ds_read_b32 v191, v3 offset:1452
	ds_read_b32 v192, v3 offset:1584
	ds_read_b32 v193, v3 offset:1716
	ds_read_b32 v194, v3 offset:1848
	ds_read_b32 v195, v3 offset:1980
	ds_read_b32 v196, v3 offset:2112
	ds_read_b32 v197, v3 offset:2244
	ds_read_b32 v198, v3 offset:2376
	ds_read_b32 v199, v3 offset:2508
	ds_read_b32 v200, v3 offset:2640
	ds_read_b32 v201, v3 offset:2772
	ds_read_b32 v202, v3 offset:2904
	ds_read_b32 v203, v3 offset:3036
	ds_read_b32 v204, v3 offset:3168
	ds_read_b32 v205, v3 offset:3300
	ds_read_b32 v206, v3 offset:3432
	ds_read_b32 v207, v3 offset:3564
	ds_read_b32 v208, v3 offset:3696
	ds_read_b32 v209, v3 offset:3828
	ds_read_b32 v210, v3 offset:3960
	ds_read_b32 v211, v3 offset:4092
	ds_read_b32 v212, v3 offset:4224
	ds_read_b32 v213, v3 offset:4356
	ds_read_b32 v214, v3 offset:4488
	ds_read_b32 v215, v3 offset:4620
	ds_read_b32 v216, v3 offset:4752
	ds_read_b32 v217, v3 offset:4884
	ds_read_b32 v218, v3 offset:5016
	ds_read_b32 v219, v3 offset:5148
	ds_read_b32 v220, v3 offset:5280
	ds_read_b32 v221, v3 offset:5412
	ds_read_b32 v222, v3 offset:5544
	ds_read_b32 v223, v3 offset:5676
	ds_read_b32 v224, v3 offset:5808
	ds_read_b32 v225, v3 offset:5940
	ds_read_b32 v226, v3 offset:6072
	ds_read_b32 v227, v3 offset:6204
	ds_read_b32 v228, v3 offset:6336
	ds_read_b32 v229, v3 offset:6468
	ds_read_b32 v230, v3 offset:6600
	ds_read_b32 v231, v3 offset:6732
	ds_read_b32 v232, v3 offset:6864
	ds_read_b32 v233, v3 offset:6996
	ds_read_b32 v234, v3 offset:7128
	ds_read_b32 v235, v3 offset:7260
	ds_read_b32 v236, v3 offset:7392
	ds_read_b32 v237, v3 offset:7524
	ds_read_b32 v238, v3 offset:7656
	ds_read_b32 v239, v3 offset:7788
	ds_read_b32 v240, v3 offset:7920
	ds_read_b32 v241, v3 offset:8052
	ds_read_b32 v242, v3 offset:8184
	ds_read_b32 v243, v3 offset:8316
	s_waitcnt vmcnt(0) lgkmcnt(0)
	v_mul_f32_e32 v180, v180, v116
	v_mul_f32_e32 v181, v181, v117
	v_mul_f32_e32 v182, v182, v118
	v_mul_f32_e32 v183, v183, v119
	v_mul_f32_e32 v184, v184, v120
	v_mul_f32_e32 v185, v185, v121
	v_mul_f32_e32 v186, v186, v122
	v_mul_f32_e32 v187, v187, v123
	v_mul_f32_e32 v188, v188, v124
	v_mul_f32_e32 v189, v189, v125
	v_mul_f32_e32 v190, v190, v126
	v_mul_f32_e32 v191, v191, v127
	v_mul_f32_e32 v192, v192, v128
	v_mul_f32_e32 v193, v193, v129
	v_mul_f32_e32 v194, v194, v130
	v_mul_f32_e32 v195, v195, v131
	v_mul_f32_e32 v196, v196, v132
	v_mul_f32_e32 v197, v197, v133
	v_mul_f32_e32 v198, v198, v134
	v_mul_f32_e32 v199, v199, v135
	v_mul_f32_e32 v200, v200, v136
	v_mul_f32_e32 v201, v201, v137
	v_mul_f32_e32 v202, v202, v138
	v_mul_f32_e32 v203, v203, v139
	v_mul_f32_e32 v204, v204, v140
	v_mul_f32_e32 v205, v205, v141
	v_mul_f32_e32 v206, v206, v142
	v_mul_f32_e32 v207, v207, v143
	v_mul_f32_e32 v208, v208, v144
	v_mul_f32_e32 v209, v209, v145
	v_mul_f32_e32 v210, v210, v146
	v_mul_f32_e32 v211, v211, v147
	v_mul_f32_e32 v212, v212, v148
	v_mul_f32_e32 v213, v213, v149
	v_mul_f32_e32 v214, v214, v150
	v_mul_f32_e32 v215, v215, v151
	v_mul_f32_e32 v216, v216, v152
	v_mul_f32_e32 v217, v217, v153
	v_mul_f32_e32 v218, v218, v154
	v_mul_f32_e32 v219, v219, v155
	v_mul_f32_e32 v220, v220, v156
	v_mul_f32_e32 v221, v221, v157
	v_mul_f32_e32 v222, v222, v158
	v_mul_f32_e32 v223, v223, v159
	v_mul_f32_e32 v224, v224, v160
	v_mul_f32_e32 v225, v225, v161
	v_mul_f32_e32 v226, v226, v162
	v_mul_f32_e32 v227, v227, v163
	v_mul_f32_e32 v228, v228, v164
	v_mul_f32_e32 v229, v229, v165
	v_mul_f32_e32 v230, v230, v166
	v_mul_f32_e32 v231, v231, v167
	v_mul_f32_e32 v232, v232, v168
	v_mul_f32_e32 v233, v233, v169
	v_mul_f32_e32 v234, v234, v170
	v_mul_f32_e32 v235, v235, v171
	v_mul_f32_e32 v236, v236, v172
	v_mul_f32_e32 v237, v237, v173
	v_mul_f32_e32 v238, v238, v174
	v_mul_f32_e32 v239, v239, v175
	v_mul_f32_e32 v240, v240, v176
	v_mul_f32_e32 v241, v241, v177
	v_mul_f32_e32 v242, v242, v178
	v_mul_f32_e32 v243, v243, v179
	s_mov_b64 s[44:45], exec
	s_andn2_b64 exec, exec, s[6:7]
	v_bfe_u32 v244, v180, 16, 1
	v_add3_u32 v180, v180, v244, s60
	v_and_b32_e32 v180, 0xffff0000, v180
; __device__ __forceinline__ unsigned f2bf(float f) { unsigned u = __builtin_bit_cast(unsigned, f); return (u + 0x7fffu + ((u >> 16) & 1u)) >> 16; }
; __device__ __forceinline__ void transpose_item(const float* W, int K, int nblk, int ldn, bf16* WT, int mode, LAS float* scr, int item, int lane, const float* lg = nullptr, const float* lb = nullptr, float* pcs = nullptr, float* pcb = nullptr) {
;     ...
;         for (int kk = 0; kk < 64; ++kk) { const float w = scr[kk * 33 + n]; const float gk = lg[k0 + kk], bk = lb[k0 + kk]; acc += (lane < 32) ? __uint_as_float(f2bf(w * gk) << 16) : w * bk; }
	v_bfe_u32 v245, v181, 16, 1
	v_add3_u32 v181, v181, v245, s60
	v_and_b32_e32 v181, 0xffff0000, v181
	v_bfe_u32 v244, v182, 16, 1
	v_add3_u32 v182, v182, v244, s60
	v_and_b32_e32 v182, 0xffff0000, v182
	v_bfe_u32 v245, v183, 16, 1
	v_add3_u32 v183, v183, v245, s60
	v_and_b32_e32 v183, 0xffff0000, v183
	v_bfe_u32 v244, v184, 16, 1
	v_add3_u32 v184, v184, v244, s60
	v_and_b32_e32 v184, 0xffff0000, v184
	v_bfe_u32 v245, v185, 16, 1
	v_add3_u32 v185, v185, v245, s60
	v_and_b32_e32 v185, 0xffff0000, v185
	v_bfe_u32 v244, v186, 16, 1
	v_add3_u32 v186, v186, v244, s60
	v_and_b32_e32 v186, 0xffff0000, v186
	v_bfe_u32 v245, v187, 16, 1
	v_add3_u32 v187, v187, v245, s60
	v_and_b32_e32 v187, 0xffff0000, v187
	v_bfe_u32 v244, v188, 16, 1
	v_add3_u32 v188, v188, v244, s60
	v_and_b32_e32 v188, 0xffff0000, v188
	v_bfe_u32 v245, v189, 16, 1
	v_add3_u32 v189, v189, v245, s60
	v_and_b32_e32 v189, 0xffff0000, v189
	v_bfe_u32 v244, v190, 16, 1
	v_add3_u32 v190, v190, v244, s60
	v_and_b32_e32 v190, 0xffff0000, v190
	v_bfe_u32 v245, v191, 16, 1
	v_add3_u32 v191, v191, v245, s60
	v_and_b32_e32 v191, 0xffff0000, v191
	v_bfe_u32 v244, v192, 16, 1
	v_add3_u32 v192, v192, v244, s60
	v_and_b32_e32 v192, 0xffff0000, v192
	v_bfe_u32 v245, v193, 16, 1
	v_add3_u32 v193, v193, v245, s60
	v_and_b32_e32 v193, 0xffff0000, v193
	v_bfe_u32 v244, v194, 16, 1
	v_add3_u32 v194, v194, v244, s60
	v_and_b32_e32 v194, 0xffff0000, v194
	v_bfe_u32 v245, v195, 16, 1
	v_add3_u32 v195, v195, v245, s60
	v_and_b32_e32 v195, 0xffff0000, v195
	v_bfe_u32 v244, v196, 16, 1
	v_add3_u32 v196, v196, v244, s60
	v_and_b32_e32 v196, 0xffff0000, v196
	v_bfe_u32 v245, v197, 16, 1
	v_add3_u32 v197, v197, v245, s60
	v_and_b32_e32 v197, 0xffff0000, v197
	v_bfe_u32 v244, v198, 16, 1
	v_add3_u32 v198, v198, v244, s60
	v_and_b32_e32 v198, 0xffff0000, v198
	v_bfe_u32 v245, v199, 16, 1
	v_add3_u32 v199, v199, v245, s60
	v_and_b32_e32 v199, 0xffff0000, v199
	v_bfe_u32 v244, v200, 16, 1
	v_add3_u32 v200, v200, v244, s60
	v_and_b32_e32 v200, 0xffff0000, v200
	v_bfe_u32 v245, v201, 16, 1
	v_add3_u32 v201, v201, v245, s60
	v_and_b32_e32 v201, 0xffff0000, v201
	v_bfe_u32 v244, v202, 16, 1
	v_add3_u32 v202, v202, v244, s60
	v_and_b32_e32 v202, 0xffff0000, v202
	v_bfe_u32 v245, v203, 16, 1
	v_add3_u32 v203, v203, v245, s60
	v_and_b32_e32 v203, 0xffff0000, v203
	v_bfe_u32 v244, v204, 16, 1
	v_add3_u32 v204, v204, v244, s60
	v_and_b32_e32 v204, 0xffff0000, v204
	v_bfe_u32 v245, v205, 16, 1
	v_add3_u32 v205, v205, v245, s60
	v_and_b32_e32 v205, 0xffff0000, v205
	v_bfe_u32 v244, v206, 16, 1
	v_add3_u32 v206, v206, v244, s60
	v_and_b32_e32 v206, 0xffff0000, v206
	v_bfe_u32 v245, v207, 16, 1
	v_add3_u32 v207, v207, v245, s60
	v_and_b32_e32 v207, 0xffff0000, v207
	v_bfe_u32 v244, v208, 16, 1
	v_add3_u32 v208, v208, v244, s60
	v_and_b32_e32 v208, 0xffff0000, v208
	v_bfe_u32 v245, v209, 16, 1
	v_add3_u32 v209, v209, v245, s60
	v_and_b32_e32 v209, 0xffff0000, v209
	v_bfe_u32 v244, v210, 16, 1
	v_add3_u32 v210, v210, v244, s60
	v_and_b32_e32 v210, 0xffff0000, v210
	v_bfe_u32 v245, v211, 16, 1
	v_add3_u32 v211, v211, v245, s60
	v_and_b32_e32 v211, 0xffff0000, v211
	v_bfe_u32 v244, v212, 16, 1
	v_add3_u32 v212, v212, v244, s60
	v_and_b32_e32 v212, 0xffff0000, v212
	v_bfe_u32 v245, v213, 16, 1
	v_add3_u32 v213, v213, v245, s60
	v_and_b32_e32 v213, 0xffff0000, v213
	v_bfe_u32 v244, v214, 16, 1
	v_add3_u32 v214, v214, v244, s60
	v_and_b32_e32 v214, 0xffff0000, v214
	v_bfe_u32 v245, v215, 16, 1
	v_add3_u32 v215, v215, v245, s60
	v_and_b32_e32 v215, 0xffff0000, v215
	v_bfe_u32 v244, v216, 16, 1
	v_add3_u32 v216, v216, v244, s60
	v_and_b32_e32 v216, 0xffff0000, v216
	v_bfe_u32 v245, v217, 16, 1
	v_add3_u32 v217, v217, v245, s60
	v_and_b32_e32 v217, 0xffff0000, v217
	v_bfe_u32 v244, v218, 16, 1
	v_add3_u32 v218, v218, v244, s60
	v_and_b32_e32 v218, 0xffff0000, v218
	v_bfe_u32 v245, v219, 16, 1
	v_add3_u32 v219, v219, v245, s60
	v_and_b32_e32 v219, 0xffff0000, v219
	v_bfe_u32 v244, v220, 16, 1
	v_add3_u32 v220, v220, v244, s60
	v_and_b32_e32 v220, 0xffff0000, v220
	v_bfe_u32 v245, v221, 16, 1
	v_add3_u32 v221, v221, v245, s60
; __device__ __forceinline__ unsigned f2bf(float f) { unsigned u = __builtin_bit_cast(unsigned, f); return (u + 0x7fffu + ((u >> 16) & 1u)) >> 16; }
; __device__ __forceinline__ void transpose_item(const float* W, int K, int nblk, int ldn, bf16* WT, int mode, LAS float* scr, int item, int lane, const float* lg = nullptr, const float* lb = nullptr, float* pcs = nullptr, float* pcb = nullptr) {
;     ...
;         for (int kk = 0; kk < 64; ++kk) { const float w = scr[kk * 33 + n]; const float gk = lg[k0 + kk], bk = lb[k0 + kk]; acc += (lane < 32) ? __uint_as_float(f2bf(w * gk) << 16) : w * bk; }
;         ((lane < 32) ? pcs : pcb)[(size_t)kb * PSTR + r0 + n] = acc; }
	v_and_b32_e32 v221, 0xffff0000, v221
	v_bfe_u32 v244, v222, 16, 1
	v_add3_u32 v222, v222, v244, s60
	v_and_b32_e32 v222, 0xffff0000, v222
	v_bfe_u32 v245, v223, 16, 1
	v_add3_u32 v223, v223, v245, s60
	v_and_b32_e32 v223, 0xffff0000, v223
	v_bfe_u32 v244, v224, 16, 1
	v_add3_u32 v224, v224, v244, s60
	v_and_b32_e32 v224, 0xffff0000, v224
	v_bfe_u32 v245, v225, 16, 1
	v_add3_u32 v225, v225, v245, s60
	v_and_b32_e32 v225, 0xffff0000, v225
	v_bfe_u32 v244, v226, 16, 1
	v_add3_u32 v226, v226, v244, s60
	v_and_b32_e32 v226, 0xffff0000, v226
	v_bfe_u32 v245, v227, 16, 1
	v_add3_u32 v227, v227, v245, s60
	v_and_b32_e32 v227, 0xffff0000, v227
	v_bfe_u32 v244, v228, 16, 1
	v_add3_u32 v228, v228, v244, s60
	v_and_b32_e32 v228, 0xffff0000, v228
	v_bfe_u32 v245, v229, 16, 1
	v_add3_u32 v229, v229, v245, s60
	v_and_b32_e32 v229, 0xffff0000, v229
	v_bfe_u32 v244, v230, 16, 1
	v_add3_u32 v230, v230, v244, s60
	v_and_b32_e32 v230, 0xffff0000, v230
	v_bfe_u32 v245, v231, 16, 1
	v_add3_u32 v231, v231, v245, s60
	v_and_b32_e32 v231, 0xffff0000, v231
	v_bfe_u32 v244, v232, 16, 1
	v_add3_u32 v232, v232, v244, s60
	v_and_b32_e32 v232, 0xffff0000, v232
	v_bfe_u32 v245, v233, 16, 1
	v_add3_u32 v233, v233, v245, s60
	v_and_b32_e32 v233, 0xffff0000, v233
	v_bfe_u32 v244, v234, 16, 1
	v_add3_u32 v234, v234, v244, s60
	v_and_b32_e32 v234, 0xffff0000, v234
	v_bfe_u32 v245, v235, 16, 1
	v_add3_u32 v235, v235, v245, s60
	v_and_b32_e32 v235, 0xffff0000, v235
	v_bfe_u32 v244, v236, 16, 1
	v_add3_u32 v236, v236, v244, s60
	v_and_b32_e32 v236, 0xffff0000, v236
	v_bfe_u32 v245, v237, 16, 1
	v_add3_u32 v237, v237, v245, s60
	v_and_b32_e32 v237, 0xffff0000, v237
	v_bfe_u32 v244, v238, 16, 1
	v_add3_u32 v238, v238, v244, s60
	v_and_b32_e32 v238, 0xffff0000, v238
	v_bfe_u32 v245, v239, 16, 1
	v_add3_u32 v239, v239, v245, s60
	v_and_b32_e32 v239, 0xffff0000, v239
	v_bfe_u32 v244, v240, 16, 1
	v_add3_u32 v240, v240, v244, s60
	v_and_b32_e32 v240, 0xffff0000, v240
	v_bfe_u32 v245, v241, 16, 1
	v_add3_u32 v241, v241, v245, s60
	v_and_b32_e32 v241, 0xffff0000, v241
	v_bfe_u32 v244, v242, 16, 1
	v_add3_u32 v242, v242, v244, s60
	v_and_b32_e32 v242, 0xffff0000, v242
	v_bfe_u32 v245, v243, 16, 1
	v_add3_u32 v243, v243, v245, s60
	v_and_b32_e32 v243, 0xffff0000, v243
	s_mov_b64 exec, s[44:45]
	v_add_f32_e32 v2, v2, v180
	v_add_f32_e32 v2, v2, v181
	v_add_f32_e32 v2, v2, v182
	v_add_f32_e32 v2, v2, v183
	v_add_f32_e32 v2, v2, v184
	v_add_f32_e32 v2, v2, v185
	v_add_f32_e32 v2, v2, v186
	v_add_f32_e32 v2, v2, v187
	v_add_f32_e32 v2, v2, v188
	v_add_f32_e32 v2, v2, v189
	v_add_f32_e32 v2, v2, v190
	v_add_f32_e32 v2, v2, v191
	v_add_f32_e32 v2, v2, v192
	v_add_f32_e32 v2, v2, v193
	v_add_f32_e32 v2, v2, v194
	v_add_f32_e32 v2, v2, v195
	v_add_f32_e32 v2, v2, v196
	v_add_f32_e32 v2, v2, v197
	v_add_f32_e32 v2, v2, v198
	v_add_f32_e32 v2, v2, v199
	v_add_f32_e32 v2, v2, v200
	v_add_f32_e32 v2, v2, v201
	v_add_f32_e32 v2, v2, v202
	v_add_f32_e32 v2, v2, v203
	v_add_f32_e32 v2, v2, v204
	v_add_f32_e32 v2, v2, v205
	v_add_f32_e32 v2, v2, v206
	v_add_f32_e32 v2, v2, v207
	v_add_f32_e32 v2, v2, v208
	v_add_f32_e32 v2, v2, v209
	v_add_f32_e32 v2, v2, v210
	v_add_f32_e32 v2, v2, v211
	v_add_f32_e32 v2, v2, v212
	v_add_f32_e32 v2, v2, v213
	v_add_f32_e32 v2, v2, v214
	v_add_f32_e32 v2, v2, v215
	v_add_f32_e32 v2, v2, v216
	v_add_f32_e32 v2, v2, v217
	v_add_f32_e32 v2, v2, v218
	v_add_f32_e32 v2, v2, v219
	v_add_f32_e32 v2, v2, v220
	v_add_f32_e32 v2, v2, v221
	v_add_f32_e32 v2, v2, v222
	v_add_f32_e32 v2, v2, v223
	v_add_f32_e32 v2, v2, v224
	v_add_f32_e32 v2, v2, v225
	v_add_f32_e32 v2, v2, v226
	v_add_f32_e32 v2, v2, v227
	v_add_f32_e32 v2, v2, v228
	v_add_f32_e32 v2, v2, v229
	v_add_f32_e32 v2, v2, v230
	v_add_f32_e32 v2, v2, v231
	v_add_f32_e32 v2, v2, v232
	v_add_f32_e32 v2, v2, v233
	v_add_f32_e32 v2, v2, v234
	v_add_f32_e32 v2, v2, v235
	v_add_f32_e32 v2, v2, v236
	v_add_f32_e32 v2, v2, v237
	v_add_f32_e32 v2, v2, v238
	v_add_f32_e32 v2, v2, v239
	v_add_f32_e32 v2, v2, v240
	v_add_f32_e32 v2, v2, v241
	v_add_f32_e32 v2, v2, v242
	v_add_f32_e32 v2, v2, v243
	s_movk_i32 s4, 0x100
	s_mov_b32 s5, 0
	s_branch .LBB0_55

; __device__ __forceinline__ unsigned f2bf(float f) { unsigned u = __builtin_bit_cast(unsigned, f); return (u + 0x7fffu + ((u >> 16) & 1u)) >> 16; }
; __device__ __forceinline__ void transpose_item(const float* W, int K, int nblk, int ldn, bf16* WT, int mode, LAS float* scr, int item, int lane, const float* lg = nullptr, const float* lb = nullptr, float* pcs = nullptr, float* pcb = nullptr) {
;     ...
;     if (lg) { const int n = lane & 31; float acc = 0.f;
; #pragma unroll 8
;         for (int kk = 0; kk < 64; ++kk) { const float w = scr[kk * 33 + n]; const float gk = lg[k0 + kk], bk = lb[k0 + kk]; acc += (lane < 32) ? __uint_as_float(f2bf(w * gk) << 16) : w * bk; }
;         ((lane < 32) ? pcs : pcb)[(size_t)kb * PSTR + r0 + n] = acc; }
.LBB0_67:
	v_mov_b32_e32 v110, s48
	v_mov_b32_e32 v111, s49
	v_mov_b32_e32 v112, s50
	v_mov_b32_e32 v113, s51
	v_mov_b32_e32 v114, v53
	v_mov_b32_e32 v115, 0
	v_cndmask_b32_e64 v110, v110, v112, s[6:7]
	v_cndmask_b32_e64 v111, v111, v113, s[6:7]
	v_lshl_add_u64 v[110:111], v[110:111], 0, v[114:115]
	global_load_dwordx4 v[116:119], v[110:111], off
	global_load_dwordx4 v[120:123], v[110:111], off offset:16
	global_load_dwordx4 v[124:127], v[110:111], off offset:32
	global_load_dwordx4 v[128:131], v[110:111], off offset:48
	global_load_dwordx4 v[132:135], v[110:111], off offset:64
	global_load_dwordx4 v[136:139], v[110:111], off offset:80
	global_load_dwordx4 v[140:143], v[110:111], off offset:96
	global_load_dwordx4 v[144:147], v[110:111], off offset:112
	global_load_dwordx4 v[148:151], v[110:111], off offset:128
	global_load_dwordx4 v[152:155], v[110:111], off offset:144
	global_load_dwordx4 v[156:159], v[110:111], off offset:160
	global_load_dwordx4 v[160:163], v[110:111], off offset:176
	global_load_dwordx4 v[164:167], v[110:111], off offset:192
	global_load_dwordx4 v[168:171], v[110:111], off offset:208
	global_load_dwordx4 v[172:175], v[110:111], off offset:224
	global_load_dwordx4 v[176:179], v[110:111], off offset:240
	ds_read_b32 v180, v3
	ds_read_b32 v181, v3 offset:132
	ds_read_b32 v182, v3 offset:264
	ds_read_b32 v183, v3 offset:396
	ds_read_b32 v184, v3 offset:528
	ds_read_b32 v185, v3 offset:660
	ds_read_b32 v186, v3 offset:792
	ds_read_b32 v187, v3 offset:924
	ds_read_b32 v188, v3 offset:1056
	ds_read_b32 v189, v3 offset:1188
	ds_read_b32 v190, v3 offset:1320
	ds_read_b32 v191, v3 offset:1452
	ds_read_b32 v192, v3 offset:1584
	ds_read_b32 v193, v3 offset:1716
	ds_read_b32 v194, v3 offset:1848
	ds_read_b32 v195, v3 offset:1980
	ds_read_b32 v196, v3 offset:2112
	ds_read_b32 v197, v3 offset:2244
	ds_read_b32 v198, v3 offset:2376
	ds_read_b32 v199, v3 offset:2508
	ds_read_b32 v200, v3 offset:2640
	ds_read_b32 v201, v3 offset:2772
	ds_read_b32 v202, v3 offset:2904
	ds_read_b32 v203, v3 offset:3036
	ds_read_b32 v204, v3 offset:3168
	ds_read_b32 v205, v3 offset:3300
	ds_read_b32 v206, v3 offset:3432
	ds_read_b32 v207, v3 offset:3564
	ds_read_b32 v208, v3 offset:3696
	ds_read_b32 v209, v3 offset:3828
	ds_read_b32 v210, v3 offset:3960
	ds_read_b32 v211, v3 offset:4092
	ds_read_b32 v212, v3 offset:4224
	ds_read_b32 v213, v3 offset:4356
	ds_read_b32 v214, v3 offset:4488
	ds_read_b32 v215, v3 offset:4620
	ds_read_b32 v216, v3 offset:4752
	ds_read_b32 v217, v3 offset:4884
	ds_read_b32 v218, v3 offset:5016
	ds_read_b32 v219, v3 offset:5148
	ds_read_b32 v220, v3 offset:5280
	ds_read_b32 v221, v3 offset:5412
	ds_read_b32 v222, v3 offset:5544
	ds_read_b32 v223, v3 offset:5676
	ds_read_b32 v224, v3 offset:5808
	ds_read_b32 v225, v3 offset:5940
	ds_read_b32 v226, v3 offset:6072
	ds_read_b32 v227, v3 offset:6204
	ds_read_b32 v228, v3 offset:6336
	ds_read_b32 v229, v3 offset:6468
	ds_read_b32 v230, v3 offset:6600
	ds_read_b32 v231, v3 offset:6732
	ds_read_b32 v232, v3 offset:6864
	ds_read_b32 v233, v3 offset:6996
	ds_read_b32 v234, v3 offset:7128
	ds_read_b32 v235, v3 offset:7260
	ds_read_b32 v236, v3 offset:7392
	ds_read_b32 v237, v3 offset:7524
	ds_read_b32 v238, v3 offset:7656
	ds_read_b32 v239, v3 offset:7788
	ds_read_b32 v240, v3 offset:7920
	ds_read_b32 v241, v3 offset:8052
	ds_read_b32 v242, v3 offset:8184
	ds_read_b32 v243, v3 offset:8316
	s_waitcnt vmcnt(0) lgkmcnt(0)
	v_mul_f32_e32 v180, v180, v116
	v_mul_f32_e32 v181, v181, v117
	v_mul_f32_e32 v182, v182, v118
	v_mul_f32_e32 v183, v183, v119
	v_mul_f32_e32 v184, v184, v120
	v_mul_f32_e32 v185, v185, v121
	v_mul_f32_e32 v186, v186, v122
	v_mul_f32_e32 v187, v187, v123
	v_mul_f32_e32 v188, v188, v124
	v_mul_f32_e32 v189, v189, v125
	v_mul_f32_e32 v190, v190, v126
	v_mul_f32_e32 v191, v191, v127
	v_mul_f32_e32 v192, v192, v128
	v_mul_f32_e32 v193, v193, v129
	v_mul_f32_e32 v194, v194, v130
	v_mul_f32_e32 v195, v195, v131
	v_mul_f32_e32 v196, v196, v132
	v_mul_f32_e32 v197, v197, v133
	v_mul_f32_e32 v198, v198, v134
	v_mul_f32_e32 v199, v199, v135
	v_mul_f32_e32 v200, v200, v136
	v_mul_f32_e32 v201, v201, v137
	v_mul_f32_e32 v202, v202, v138
	v_mul_f32_e32 v203, v203, v139
	v_mul_f32_e32 v204, v204, v140
	v_mul_f32_e32 v205, v205, v141
	v_mul_f32_e32 v206, v206, v142
	v_mul_f32_e32 v207, v207, v143
	v_mul_f32_e32 v208, v208, v144
	v_mul_f32_e32 v209, v209, v145
	v_mul_f32_e32 v210, v210, v146
	v_mul_f32_e32 v211, v211, v147
	v_mul_f32_e32 v212, v212, v148
	v_mul_f32_e32 v213, v213, v149
	v_mul_f32_e32 v214, v214, v150
	v_mul_f32_e32 v215, v215, v151
	v_mul_f32_e32 v216, v216, v152
	v_mul_f32_e32 v217, v217, v153
	v_mul_f32_e32 v218, v218, v154
	v_mul_f32_e32 v219, v219, v155
	v_mul_f32_e32 v220, v220, v156
	v_mul_f32_e32 v221, v221, v157
	v_mul_f32_e32 v222, v222, v158
	v_mul_f32_e32 v223, v223, v159
	v_mul_f32_e32 v224, v224, v160
	v_mul_f32_e32 v225, v225, v161
	v_mul_f32_e32 v226, v226, v162
	v_mul_f32_e32 v227, v227, v163
	v_mul_f32_e32 v228, v228, v164
	v_mul_f32_e32 v229, v229, v165
	v_mul_f32_e32 v230, v230, v166
	v_mul_f32_e32 v231, v231, v167
	v_mul_f32_e32 v232, v232, v168
	v_mul_f32_e32 v233, v233, v169
	v_mul_f32_e32 v234, v234, v170
	v_mul_f32_e32 v235, v235, v171
	v_mul_f32_e32 v236, v236, v172
	v_mul_f32_e32 v237, v237, v173
	v_mul_f32_e32 v238, v238, v174
	v_mul_f32_e32 v239, v239, v175
	v_mul_f32_e32 v240, v240, v176
	v_mul_f32_e32 v241, v241, v177
	v_mul_f32_e32 v242, v242, v178
	v_mul_f32_e32 v243, v243, v179
	s_mov_b64 s[44:45], exec
	s_andn2_b64 exec, exec, s[6:7]
	v_bfe_u32 v244, v180, 16, 1
	v_add3_u32 v180, v180, v244, s60
	v_and_b32_e32 v180, 0xffff0000, v180
; __device__ __forceinline__ unsigned f2bf(float f) { unsigned u = __builtin_bit_cast(unsigned, f); return (u + 0x7fffu + ((u >> 16) & 1u)) >> 16; }
; __device__ __forceinline__ void transpose_item(const float* W, int K, int nblk, int ldn, bf16* WT, int mode, LAS float* scr, int item, int lane, const float* lg = nullptr, const float* lb = nullptr, float* pcs = nullptr, float* pcb = nullptr) {
;     ...
;         for (int kk = 0; kk < 64; ++kk) { const float w = scr[kk * 33 + n]; const float gk = lg[k0 + kk], bk = lb[k0 + kk]; acc += (lane < 32) ? __uint_as_float(f2bf(w * gk) << 16) : w * bk; }
	v_bfe_u32 v245, v181, 16, 1
	v_add3_u32 v181, v181, v245, s60
	v_and_b32_e32 v181, 0xffff0000, v181
	v_bfe_u32 v244, v182, 16, 1
	v_add3_u32 v182, v182, v244, s60
	v_and_b32_e32 v182, 0xffff0000, v182
	v_bfe_u32 v245, v183, 16, 1
	v_add3_u32 v183, v183, v245, s60
	v_and_b32_e32 v183, 0xffff0000, v183
	v_bfe_u32 v244, v184, 16, 1
	v_add3_u32 v184, v184, v244, s60
	v_and_b32_e32 v184, 0xffff0000, v184
	v_bfe_u32 v245, v185, 16, 1
	v_add3_u32 v185, v185, v245, s60
	v_and_b32_e32 v185, 0xffff0000, v185
	v_bfe_u32 v244, v186, 16, 1
	v_add3_u32 v186, v186, v244, s60
	v_and_b32_e32 v186, 0xffff0000, v186
	v_bfe_u32 v245, v187, 16, 1
	v_add3_u32 v187, v187, v245, s60
	v_and_b32_e32 v187, 0xffff0000, v187
	v_bfe_u32 v244, v188, 16, 1
	v_add3_u32 v188, v188, v244, s60
	v_and_b32_e32 v188, 0xffff0000, v188
	v_bfe_u32 v245, v189, 16, 1
	v_add3_u32 v189, v189, v245, s60
	v_and_b32_e32 v189, 0xffff0000, v189
	v_bfe_u32 v244, v190, 16, 1
	v_add3_u32 v190, v190, v244, s60
	v_and_b32_e32 v190, 0xffff0000, v190
	v_bfe_u32 v245, v191, 16, 1
	v_add3_u32 v191, v191, v245, s60
	v_and_b32_e32 v191, 0xffff0000, v191
	v_bfe_u32 v244, v192, 16, 1
	v_add3_u32 v192, v192, v244, s60
	v_and_b32_e32 v192, 0xffff0000, v192
	v_bfe_u32 v245, v193, 16, 1
	v_add3_u32 v193, v193, v245, s60
	v_and_b32_e32 v193, 0xffff0000, v193
	v_bfe_u32 v244, v194, 16, 1
	v_add3_u32 v194, v194, v244, s60
	v_and_b32_e32 v194, 0xffff0000, v194
	v_bfe_u32 v245, v195, 16, 1
	v_add3_u32 v195, v195, v245, s60
	v_and_b32_e32 v195, 0xffff0000, v195
	v_bfe_u32 v244, v196, 16, 1
	v_add3_u32 v196, v196, v244, s60
	v_and_b32_e32 v196, 0xffff0000, v196
	v_bfe_u32 v245, v197, 16, 1
	v_add3_u32 v197, v197, v245, s60
	v_and_b32_e32 v197, 0xffff0000, v197
	v_bfe_u32 v244, v198, 16, 1
	v_add3_u32 v198, v198, v244, s60
	v_and_b32_e32 v198, 0xffff0000, v198
	v_bfe_u32 v245, v199, 16, 1
	v_add3_u32 v199, v199, v245, s60
	v_and_b32_e32 v199, 0xffff0000, v199
	v_bfe_u32 v244, v200, 16, 1
	v_add3_u32 v200, v200, v244, s60
	v_and_b32_e32 v200, 0xffff0000, v200
	v_bfe_u32 v245, v201, 16, 1
	v_add3_u32 v201, v201, v245, s60
	v_and_b32_e32 v201, 0xffff0000, v201
	v_bfe_u32 v244, v202, 16, 1
	v_add3_u32 v202, v202, v244, s60
	v_and_b32_e32 v202, 0xffff0000, v202
	v_bfe_u32 v245, v203, 16, 1
	v_add3_u32 v203, v203, v245, s60
	v_and_b32_e32 v203, 0xffff0000, v203
	v_bfe_u32 v244, v204, 16, 1
	v_add3_u32 v204, v204, v244, s60
	v_and_b32_e32 v204, 0xffff0000, v204
	v_bfe_u32 v245, v205, 16, 1
	v_add3_u32 v205, v205, v245, s60
	v_and_b32_e32 v205, 0xffff0000, v205
	v_bfe_u32 v244, v206, 16, 1
	v_add3_u32 v206, v206, v244, s60
	v_and_b32_e32 v206, 0xffff0000, v206
	v_bfe_u32 v245, v207, 16, 1
	v_add3_u32 v207, v207, v245, s60
	v_and_b32_e32 v207, 0xffff0000, v207
	v_bfe_u32 v244, v208, 16, 1
	v_add3_u32 v208, v208, v244, s60
	v_and_b32_e32 v208, 0xffff0000, v208
	v_bfe_u32 v245, v209, 16, 1
	v_add3_u32 v209, v209, v245, s60
	v_and_b32_e32 v209, 0xffff0000, v209
	v_bfe_u32 v244, v210, 16, 1
	v_add3_u32 v210, v210, v244, s60
	v_and_b32_e32 v210, 0xffff0000, v210
	v_bfe_u32 v245, v211, 16, 1
	v_add3_u32 v211, v211, v245, s60
	v_and_b32_e32 v211, 0xffff0000, v211
	v_bfe_u32 v244, v212, 16, 1
	v_add3_u32 v212, v212, v244, s60
	v_and_b32_e32 v212, 0xffff0000, v212
	v_bfe_u32 v245, v213, 16, 1
	v_add3_u32 v213, v213, v245, s60
	v_and_b32_e32 v213, 0xffff0000, v213
	v_bfe_u32 v244, v214, 16, 1
	v_add3_u32 v214, v214, v244, s60
	v_and_b32_e32 v214, 0xffff0000, v214
	v_bfe_u32 v245, v215, 16, 1
	v_add3_u32 v215, v215, v245, s60
	v_and_b32_e32 v215, 0xffff0000, v215
	v_bfe_u32 v244, v216, 16, 1
	v_add3_u32 v216, v216, v244, s60
	v_and_b32_e32 v216, 0xffff0000, v216
	v_bfe_u32 v245, v217, 16, 1
	v_add3_u32 v217, v217, v245, s60
	v_and_b32_e32 v217, 0xffff0000, v217
	v_bfe_u32 v244, v218, 16, 1
	v_add3_u32 v218, v218, v244, s60
	v_and_b32_e32 v218, 0xffff0000, v218
	v_bfe_u32 v245, v219, 16, 1
	v_add3_u32 v219, v219, v245, s60
	v_and_b32_e32 v219, 0xffff0000, v219
	v_bfe_u32 v244, v220, 16, 1
	v_add3_u32 v220, v220, v244, s60
	v_and_b32_e32 v220, 0xffff0000, v220
	v_bfe_u32 v245, v221, 16, 1
	v_add3_u32 v221, v221, v245, s60
; __device__ __forceinline__ unsigned f2bf(float f) { unsigned u = __builtin_bit_cast(unsigned, f); return (u + 0x7fffu + ((u >> 16) & 1u)) >> 16; }
; __device__ __forceinline__ void transpose_item(const float* W, int K, int nblk, int ldn, bf16* WT, int mode, LAS float* scr, int item, int lane, const float* lg = nullptr, const float* lb = nullptr, float* pcs = nullptr, float* pcb = nullptr) {
;     ...
;         for (int kk = 0; kk < 64; ++kk) { const float w = scr[kk * 33 + n]; const float gk = lg[k0 + kk], bk = lb[k0 + kk]; acc += (lane < 32) ? __uint_as_float(f2bf(w * gk) << 16) : w * bk; }
;         ((lane < 32) ? pcs : pcb)[(size_t)kb * PSTR + r0 + n] = acc; }
	v_and_b32_e32 v221, 0xffff0000, v221
	v_bfe_u32 v244, v222, 16, 1
	v_add3_u32 v222, v222, v244, s60
	v_and_b32_e32 v222, 0xffff0000, v222
	v_bfe_u32 v245, v223, 16, 1
	v_add3_u32 v223, v223, v245, s60
	v_and_b32_e32 v223, 0xffff0000, v223
	v_bfe_u32 v244, v224, 16, 1
	v_add3_u32 v224, v224, v244, s60
	v_and_b32_e32 v224, 0xffff0000, v224
	v_bfe_u32 v245, v225, 16, 1
	v_add3_u32 v225, v225, v245, s60
	v_and_b32_e32 v225, 0xffff0000, v225
	v_bfe_u32 v244, v226, 16, 1
	v_add3_u32 v226, v226, v244, s60
	v_and_b32_e32 v226, 0xffff0000, v226
	v_bfe_u32 v245, v227, 16, 1
	v_add3_u32 v227, v227, v245, s60
	v_and_b32_e32 v227, 0xffff0000, v227
	v_bfe_u32 v244, v228, 16, 1
	v_add3_u32 v228, v228, v244, s60
	v_and_b32_e32 v228, 0xffff0000, v228
	v_bfe_u32 v245, v229, 16, 1
	v_add3_u32 v229, v229, v245, s60
	v_and_b32_e32 v229, 0xffff0000, v229
	v_bfe_u32 v244, v230, 16, 1
	v_add3_u32 v230, v230, v244, s60
	v_and_b32_e32 v230, 0xffff0000, v230
	v_bfe_u32 v245, v231, 16, 1
	v_add3_u32 v231, v231, v245, s60
	v_and_b32_e32 v231, 0xffff0000, v231
	v_bfe_u32 v244, v232, 16, 1
	v_add3_u32 v232, v232, v244, s60
	v_and_b32_e32 v232, 0xffff0000, v232
	v_bfe_u32 v245, v233, 16, 1
	v_add3_u32 v233, v233, v245, s60
	v_and_b32_e32 v233, 0xffff0000, v233
	v_bfe_u32 v244, v234, 16, 1
	v_add3_u32 v234, v234, v244, s60
	v_and_b32_e32 v234, 0xffff0000, v234
	v_bfe_u32 v245, v235, 16, 1
	v_add3_u32 v235, v235, v245, s60
	v_and_b32_e32 v235, 0xffff0000, v235
	v_bfe_u32 v244, v236, 16, 1
	v_add3_u32 v236, v236, v244, s60
	v_and_b32_e32 v236, 0xffff0000, v236
	v_bfe_u32 v245, v237, 16, 1
	v_add3_u32 v237, v237, v245, s60
	v_and_b32_e32 v237, 0xffff0000, v237
	v_bfe_u32 v244, v238, 16, 1
	v_add3_u32 v238, v238, v244, s60
	v_and_b32_e32 v238, 0xffff0000, v238
	v_bfe_u32 v245, v239, 16, 1
	v_add3_u32 v239, v239, v245, s60
	v_and_b32_e32 v239, 0xffff0000, v239
	v_bfe_u32 v244, v240, 16, 1
	v_add3_u32 v240, v240, v244, s60
	v_and_b32_e32 v240, 0xffff0000, v240
	v_bfe_u32 v245, v241, 16, 1
	v_add3_u32 v241, v241, v245, s60
	v_and_b32_e32 v241, 0xffff0000, v241
	v_bfe_u32 v244, v242, 16, 1
	v_add3_u32 v242, v242, v244, s60
	v_and_b32_e32 v242, 0xffff0000, v242
	v_bfe_u32 v245, v243, 16, 1
	v_add3_u32 v243, v243, v245, s60
	v_and_b32_e32 v243, 0xffff0000, v243
	s_mov_b64 exec, s[44:45]
	v_add_f32_e32 v2, v2, v180
	v_add_f32_e32 v2, v2, v181
	v_add_f32_e32 v2, v2, v182
	v_add_f32_e32 v2, v2, v183
	v_add_f32_e32 v2, v2, v184
	v_add_f32_e32 v2, v2, v185
	v_add_f32_e32 v2, v2, v186
	v_add_f32_e32 v2, v2, v187
	v_add_f32_e32 v2, v2, v188
	v_add_f32_e32 v2, v2, v189
	v_add_f32_e32 v2, v2, v190
	v_add_f32_e32 v2, v2, v191
	v_add_f32_e32 v2, v2, v192
	v_add_f32_e32 v2, v2, v193
	v_add_f32_e32 v2, v2, v194
	v_add_f32_e32 v2, v2, v195
	v_add_f32_e32 v2, v2, v196
	v_add_f32_e32 v2, v2, v197
	v_add_f32_e32 v2, v2, v198
	v_add_f32_e32 v2, v2, v199
	v_add_f32_e32 v2, v2, v200
	v_add_f32_e32 v2, v2, v201
	v_add_f32_e32 v2, v2, v202
	v_add_f32_e32 v2, v2, v203
	v_add_f32_e32 v2, v2, v204
	v_add_f32_e32 v2, v2, v205
	v_add_f32_e32 v2, v2, v206
	v_add_f32_e32 v2, v2, v207
	v_add_f32_e32 v2, v2, v208
	v_add_f32_e32 v2, v2, v209
	v_add_f32_e32 v2, v2, v210
	v_add_f32_e32 v2, v2, v211
	v_add_f32_e32 v2, v2, v212
	v_add_f32_e32 v2, v2, v213
	v_add_f32_e32 v2, v2, v214
	v_add_f32_e32 v2, v2, v215
	v_add_f32_e32 v2, v2, v216
	v_add_f32_e32 v2, v2, v217
	v_add_f32_e32 v2, v2, v218
	v_add_f32_e32 v2, v2, v219
	v_add_f32_e32 v2, v2, v220
	v_add_f32_e32 v2, v2, v221
	v_add_f32_e32 v2, v2, v222
	v_add_f32_e32 v2, v2, v223
	v_add_f32_e32 v2, v2, v224
	v_add_f32_e32 v2, v2, v225
	v_add_f32_e32 v2, v2, v226
	v_add_f32_e32 v2, v2, v227
	v_add_f32_e32 v2, v2, v228
	v_add_f32_e32 v2, v2, v229
	v_add_f32_e32 v2, v2, v230
	v_add_f32_e32 v2, v2, v231
	v_add_f32_e32 v2, v2, v232
	v_add_f32_e32 v2, v2, v233
	v_add_f32_e32 v2, v2, v234
	v_add_f32_e32 v2, v2, v235
	v_add_f32_e32 v2, v2, v236
	v_add_f32_e32 v2, v2, v237
	v_add_f32_e32 v2, v2, v238
	v_add_f32_e32 v2, v2, v239
	v_add_f32_e32 v2, v2, v240
	v_add_f32_e32 v2, v2, v241
	v_add_f32_e32 v2, v2, v242
	v_add_f32_e32 v2, v2, v243
	s_movk_i32 s4, 0x100
	s_mov_b32 s5, 0
	s_branch .LBB0_99

; __device__ __forceinline__ unsigned f2bf(float f) { unsigned u = __builtin_bit_cast(unsigned, f); return (u + 0x7fffu + ((u >> 16) & 1u)) >> 16; }
; __device__ __forceinline__ void transpose_item(const float* W, int K, int nblk, int ldn, bf16* WT, int mode, LAS float* scr, int item, int lane, const float* lg = nullptr, const float* lb = nullptr, float* pcs = nullptr, float* pcb = nullptr) {
;     ...
;     if (lg) { const int n = lane & 31; float acc = 0.f;
; #pragma unroll 8
;         for (int kk = 0; kk < 64; ++kk) { const float w = scr[kk * 33 + n]; const float gk = lg[k0 + kk], bk = lb[k0 + kk]; acc += (lane < 32) ? __uint_as_float(f2bf(w * gk) << 16) : w * bk; }
;         ((lane < 32) ? pcs : pcb)[(size_t)kb * PSTR + r0 + n] = acc; }
.LBB0_119:
	v_mov_b32_e32 v110, s42
	v_mov_b32_e32 v111, s45
	v_mov_b32_e32 v112, s49
	v_mov_b32_e32 v113, s50
	v_mov_b32_e32 v114, v15
	v_mov_b32_e32 v115, 0
	v_cndmask_b32_e64 v110, v110, v112, s[6:7]
	v_cndmask_b32_e64 v111, v111, v113, s[6:7]
	v_lshl_add_u64 v[110:111], v[110:111], 0, v[114:115]
	global_load_dwordx4 v[116:119], v[110:111], off
	global_load_dwordx4 v[120:123], v[110:111], off offset:16
	global_load_dwordx4 v[124:127], v[110:111], off offset:32
	global_load_dwordx4 v[128:131], v[110:111], off offset:48
	global_load_dwordx4 v[132:135], v[110:111], off offset:64
	global_load_dwordx4 v[136:139], v[110:111], off offset:80
	global_load_dwordx4 v[140:143], v[110:111], off offset:96
	global_load_dwordx4 v[144:147], v[110:111], off offset:112
	global_load_dwordx4 v[148:151], v[110:111], off offset:128
	global_load_dwordx4 v[152:155], v[110:111], off offset:144
	global_load_dwordx4 v[156:159], v[110:111], off offset:160
	global_load_dwordx4 v[160:163], v[110:111], off offset:176
	global_load_dwordx4 v[164:167], v[110:111], off offset:192
	global_load_dwordx4 v[168:171], v[110:111], off offset:208
	global_load_dwordx4 v[172:175], v[110:111], off offset:224
	global_load_dwordx4 v[176:179], v[110:111], off offset:240
	ds_read_b32 v180, v3
	ds_read_b32 v181, v3 offset:132
	ds_read_b32 v182, v3 offset:264
	ds_read_b32 v183, v3 offset:396
	ds_read_b32 v184, v3 offset:528
	ds_read_b32 v185, v3 offset:660
	ds_read_b32 v186, v3 offset:792
	ds_read_b32 v187, v3 offset:924
	ds_read_b32 v188, v3 offset:1056
	ds_read_b32 v189, v3 offset:1188
	ds_read_b32 v190, v3 offset:1320
	ds_read_b32 v191, v3 offset:1452
	ds_read_b32 v192, v3 offset:1584
	ds_read_b32 v193, v3 offset:1716
	ds_read_b32 v194, v3 offset:1848
	ds_read_b32 v195, v3 offset:1980
	ds_read_b32 v196, v3 offset:2112
	ds_read_b32 v197, v3 offset:2244
	ds_read_b32 v198, v3 offset:2376
	ds_read_b32 v199, v3 offset:2508
	ds_read_b32 v200, v3 offset:2640
	ds_read_b32 v201, v3 offset:2772
	ds_read_b32 v202, v3 offset:2904
	ds_read_b32 v203, v3 offset:3036
	ds_read_b32 v204, v3 offset:3168
	ds_read_b32 v205, v3 offset:3300
	ds_read_b32 v206, v3 offset:3432
	ds_read_b32 v207, v3 offset:3564
	ds_read_b32 v208, v3 offset:3696
	ds_read_b32 v209, v3 offset:3828
	ds_read_b32 v210, v3 offset:3960
	ds_read_b32 v211, v3 offset:4092
	ds_read_b32 v212, v3 offset:4224
	ds_read_b32 v213, v3 offset:4356
	ds_read_b32 v214, v3 offset:4488
	ds_read_b32 v215, v3 offset:4620
	ds_read_b32 v216, v3 offset:4752
	ds_read_b32 v217, v3 offset:4884
	ds_read_b32 v218, v3 offset:5016
	ds_read_b32 v219, v3 offset:5148
	ds_read_b32 v220, v3 offset:5280
	ds_read_b32 v221, v3 offset:5412
	ds_read_b32 v222, v3 offset:5544
	ds_read_b32 v223, v3 offset:5676
	ds_read_b32 v224, v3 offset:5808
	ds_read_b32 v225, v3 offset:5940
	ds_read_b32 v226, v3 offset:6072
	ds_read_b32 v227, v3 offset:6204
	ds_read_b32 v228, v3 offset:6336
	ds_read_b32 v229, v3 offset:6468
	ds_read_b32 v230, v3 offset:6600
	ds_read_b32 v231, v3 offset:6732
	ds_read_b32 v232, v3 offset:6864
	ds_read_b32 v233, v3 offset:6996
	ds_read_b32 v234, v3 offset:7128
	ds_read_b32 v235, v3 offset:7260
	ds_read_b32 v236, v3 offset:7392
	ds_read_b32 v237, v3 offset:7524
	ds_read_b32 v238, v3 offset:7656
	ds_read_b32 v239, v3 offset:7788
	ds_read_b32 v240, v3 offset:7920
	ds_read_b32 v241, v3 offset:8052
	ds_read_b32 v242, v3 offset:8184
	ds_read_b32 v243, v3 offset:8316
	s_waitcnt vmcnt(0) lgkmcnt(0)
	v_mul_f32_e32 v180, v180, v116
	v_mul_f32_e32 v181, v181, v117
	v_mul_f32_e32 v182, v182, v118
	v_mul_f32_e32 v183, v183, v119
	v_mul_f32_e32 v184, v184, v120
	v_mul_f32_e32 v185, v185, v121
	v_mul_f32_e32 v186, v186, v122
	v_mul_f32_e32 v187, v187, v123
	v_mul_f32_e32 v188, v188, v124
	v_mul_f32_e32 v189, v189, v125
	v_mul_f32_e32 v190, v190, v126
	v_mul_f32_e32 v191, v191, v127
	v_mul_f32_e32 v192, v192, v128
	v_mul_f32_e32 v193, v193, v129
	v_mul_f32_e32 v194, v194, v130
	v_mul_f32_e32 v195, v195, v131
	v_mul_f32_e32 v196, v196, v132
	v_mul_f32_e32 v197, v197, v133
	v_mul_f32_e32 v198, v198, v134
	v_mul_f32_e32 v199, v199, v135
	v_mul_f32_e32 v200, v200, v136
	v_mul_f32_e32 v201, v201, v137
	v_mul_f32_e32 v202, v202, v138
	v_mul_f32_e32 v203, v203, v139
	v_mul_f32_e32 v204, v204, v140
	v_mul_f32_e32 v205, v205, v141
	v_mul_f32_e32 v206, v206, v142
	v_mul_f32_e32 v207, v207, v143
	v_mul_f32_e32 v208, v208, v144
	v_mul_f32_e32 v209, v209, v145
	v_mul_f32_e32 v210, v210, v146
	v_mul_f32_e32 v211, v211, v147
	v_mul_f32_e32 v212, v212, v148
	v_mul_f32_e32 v213, v213, v149
	v_mul_f32_e32 v214, v214, v150
	v_mul_f32_e32 v215, v215, v151
	v_mul_f32_e32 v216, v216, v152
	v_mul_f32_e32 v217, v217, v153
	v_mul_f32_e32 v218, v218, v154
	v_mul_f32_e32 v219, v219, v155
	v_mul_f32_e32 v220, v220, v156
	v_mul_f32_e32 v221, v221, v157
	v_mul_f32_e32 v222, v222, v158
	v_mul_f32_e32 v223, v223, v159
	v_mul_f32_e32 v224, v224, v160
	v_mul_f32_e32 v225, v225, v161
	v_mul_f32_e32 v226, v226, v162
	v_mul_f32_e32 v227, v227, v163
	v_mul_f32_e32 v228, v228, v164
	v_mul_f32_e32 v229, v229, v165
	v_mul_f32_e32 v230, v230, v166
	v_mul_f32_e32 v231, v231, v167
	v_mul_f32_e32 v232, v232, v168
	v_mul_f32_e32 v233, v233, v169
	v_mul_f32_e32 v234, v234, v170
	v_mul_f32_e32 v235, v235, v171
	v_mul_f32_e32 v236, v236, v172
	v_mul_f32_e32 v237, v237, v173
	v_mul_f32_e32 v238, v238, v174
	v_mul_f32_e32 v239, v239, v175
	v_mul_f32_e32 v240, v240, v176
	v_mul_f32_e32 v241, v241, v177
	v_mul_f32_e32 v242, v242, v178
	v_mul_f32_e32 v243, v243, v179
	s_mov_b64 s[46:47], exec
	s_andn2_b64 exec, exec, s[6:7]
	v_bfe_u32 v244, v180, 16, 1
	v_add3_u32 v180, v180, v244, s60
	v_and_b32_e32 v180, 0xffff0000, v180
; __device__ __forceinline__ unsigned f2bf(float f) { unsigned u = __builtin_bit_cast(unsigned, f); return (u + 0x7fffu + ((u >> 16) & 1u)) >> 16; }
; __device__ __forceinline__ void transpose_item(const float* W, int K, int nblk, int ldn, bf16* WT, int mode, LAS float* scr, int item, int lane, const float* lg = nullptr, const float* lb = nullptr, float* pcs = nullptr, float* pcb = nullptr) {
;     ...
;         for (int kk = 0; kk < 64; ++kk) { const float w = scr[kk * 33 + n]; const float gk = lg[k0 + kk], bk = lb[k0 + kk]; acc += (lane < 32) ? __uint_as_float(f2bf(w * gk) << 16) : w * bk; }
	v_bfe_u32 v245, v181, 16, 1
	v_add3_u32 v181, v181, v245, s60
	v_and_b32_e32 v181, 0xffff0000, v181
	v_bfe_u32 v244, v182, 16, 1
	v_add3_u32 v182, v182, v244, s60
	v_and_b32_e32 v182, 0xffff0000, v182
	v_bfe_u32 v245, v183, 16, 1
	v_add3_u32 v183, v183, v245, s60
	v_and_b32_e32 v183, 0xffff0000, v183
	v_bfe_u32 v244, v184, 16, 1
	v_add3_u32 v184, v184, v244, s60
	v_and_b32_e32 v184, 0xffff0000, v184
	v_bfe_u32 v245, v185, 16, 1
	v_add3_u32 v185, v185, v245, s60
	v_and_b32_e32 v185, 0xffff0000, v185
	v_bfe_u32 v244, v186, 16, 1
	v_add3_u32 v186, v186, v244, s60
	v_and_b32_e32 v186, 0xffff0000, v186
	v_bfe_u32 v245, v187, 16, 1
	v_add3_u32 v187, v187, v245, s60
	v_and_b32_e32 v187, 0xffff0000, v187
	v_bfe_u32 v244, v188, 16, 1
	v_add3_u32 v188, v188, v244, s60
	v_and_b32_e32 v188, 0xffff0000, v188
	v_bfe_u32 v245, v189, 16, 1
	v_add3_u32 v189, v189, v245, s60
	v_and_b32_e32 v189, 0xffff0000, v189
	v_bfe_u32 v244, v190, 16, 1
	v_add3_u32 v190, v190, v244, s60
	v_and_b32_e32 v190, 0xffff0000, v190
	v_bfe_u32 v245, v191, 16, 1
	v_add3_u32 v191, v191, v245, s60
	v_and_b32_e32 v191, 0xffff0000, v191
	v_bfe_u32 v244, v192, 16, 1
	v_add3_u32 v192, v192, v244, s60
	v_and_b32_e32 v192, 0xffff0000, v192
	v_bfe_u32 v245, v193, 16, 1
	v_add3_u32 v193, v193, v245, s60
	v_and_b32_e32 v193, 0xffff0000, v193
	v_bfe_u32 v244, v194, 16, 1
	v_add3_u32 v194, v194, v244, s60
	v_and_b32_e32 v194, 0xffff0000, v194
	v_bfe_u32 v245, v195, 16, 1
	v_add3_u32 v195, v195, v245, s60
	v_and_b32_e32 v195, 0xffff0000, v195
	v_bfe_u32 v244, v196, 16, 1
	v_add3_u32 v196, v196, v244, s60
	v_and_b32_e32 v196, 0xffff0000, v196
	v_bfe_u32 v245, v197, 16, 1
	v_add3_u32 v197, v197, v245, s60
	v_and_b32_e32 v197, 0xffff0000, v197
	v_bfe_u32 v244, v198, 16, 1
	v_add3_u32 v198, v198, v244, s60
	v_and_b32_e32 v198, 0xffff0000, v198
	v_bfe_u32 v245, v199, 16, 1
	v_add3_u32 v199, v199, v245, s60
	v_and_b32_e32 v199, 0xffff0000, v199
	v_bfe_u32 v244, v200, 16, 1
	v_add3_u32 v200, v200, v244, s60
	v_and_b32_e32 v200, 0xffff0000, v200
	v_bfe_u32 v245, v201, 16, 1
	v_add3_u32 v201, v201, v245, s60
	v_and_b32_e32 v201, 0xffff0000, v201
	v_bfe_u32 v244, v202, 16, 1
	v_add3_u32 v202, v202, v244, s60
	v_and_b32_e32 v202, 0xffff0000, v202
	v_bfe_u32 v245, v203, 16, 1
	v_add3_u32 v203, v203, v245, s60
	v_and_b32_e32 v203, 0xffff0000, v203
	v_bfe_u32 v244, v204, 16, 1
	v_add3_u32 v204, v204, v244, s60
	v_and_b32_e32 v204, 0xffff0000, v204
	v_bfe_u32 v245, v205, 16, 1
	v_add3_u32 v205, v205, v245, s60
	v_and_b32_e32 v205, 0xffff0000, v205
	v_bfe_u32 v244, v206, 16, 1
	v_add3_u32 v206, v206, v244, s60
	v_and_b32_e32 v206, 0xffff0000, v206
	v_bfe_u32 v245, v207, 16, 1
	v_add3_u32 v207, v207, v245, s60
	v_and_b32_e32 v207, 0xffff0000, v207
	v_bfe_u32 v244, v208, 16, 1
	v_add3_u32 v208, v208, v244, s60
	v_and_b32_e32 v208, 0xffff0000, v208
	v_bfe_u32 v245, v209, 16, 1
	v_add3_u32 v209, v209, v245, s60
	v_and_b32_e32 v209, 0xffff0000, v209
	v_bfe_u32 v244, v210, 16, 1
	v_add3_u32 v210, v210, v244, s60
	v_and_b32_e32 v210, 0xffff0000, v210
	v_bfe_u32 v245, v211, 16, 1
	v_add3_u32 v211, v211, v245, s60
	v_and_b32_e32 v211, 0xffff0000, v211
	v_bfe_u32 v244, v212, 16, 1
	v_add3_u32 v212, v212, v244, s60
	v_and_b32_e32 v212, 0xffff0000, v212
	v_bfe_u32 v245, v213, 16, 1
	v_add3_u32 v213, v213, v245, s60
	v_and_b32_e32 v213, 0xffff0000, v213
	v_bfe_u32 v244, v214, 16, 1
	v_add3_u32 v214, v214, v244, s60
	v_and_b32_e32 v214, 0xffff0000, v214
	v_bfe_u32 v245, v215, 16, 1
	v_add3_u32 v215, v215, v245, s60
	v_and_b32_e32 v215, 0xffff0000, v215
	v_bfe_u32 v244, v216, 16, 1
	v_add3_u32 v216, v216, v244, s60
	v_and_b32_e32 v216, 0xffff0000, v216
	v_bfe_u32 v245, v217, 16, 1
	v_add3_u32 v217, v217, v245, s60
	v_and_b32_e32 v217, 0xffff0000, v217
	v_bfe_u32 v244, v218, 16, 1
	v_add3_u32 v218, v218, v244, s60
	v_and_b32_e32 v218, 0xffff0000, v218
	v_bfe_u32 v245, v219, 16, 1
	v_add3_u32 v219, v219, v245, s60
	v_and_b32_e32 v219, 0xffff0000, v219
	v_bfe_u32 v244, v220, 16, 1
	v_add3_u32 v220, v220, v244, s60
	v_and_b32_e32 v220, 0xffff0000, v220
	v_bfe_u32 v245, v221, 16, 1
	v_add3_u32 v221, v221, v245, s60
; __device__ __forceinline__ unsigned f2bf(float f) { unsigned u = __builtin_bit_cast(unsigned, f); return (u + 0x7fffu + ((u >> 16) & 1u)) >> 16; }
; __device__ __forceinline__ void transpose_item(const float* W, int K, int nblk, int ldn, bf16* WT, int mode, LAS float* scr, int item, int lane, const float* lg = nullptr, const float* lb = nullptr, float* pcs = nullptr, float* pcb = nullptr) {
;     ...
;         for (int kk = 0; kk < 64; ++kk) { const float w = scr[kk * 33 + n]; const float gk = lg[k0 + kk], bk = lb[k0 + kk]; acc += (lane < 32) ? __uint_as_float(f2bf(w * gk) << 16) : w * bk; }
;         ((lane < 32) ? pcs : pcb)[(size_t)kb * PSTR + r0 + n] = acc; }
	v_and_b32_e32 v221, 0xffff0000, v221
	v_bfe_u32 v244, v222, 16, 1
	v_add3_u32 v222, v222, v244, s60
	v_and_b32_e32 v222, 0xffff0000, v222
	v_bfe_u32 v245, v223, 16, 1
	v_add3_u32 v223, v223, v245, s60
	v_and_b32_e32 v223, 0xffff0000, v223
	v_bfe_u32 v244, v224, 16, 1
	v_add3_u32 v224, v224, v244, s60
	v_and_b32_e32 v224, 0xffff0000, v224
	v_bfe_u32 v245, v225, 16, 1
	v_add3_u32 v225, v225, v245, s60
	v_and_b32_e32 v225, 0xffff0000, v225
	v_bfe_u32 v244, v226, 16, 1
	v_add3_u32 v226, v226, v244, s60
	v_and_b32_e32 v226, 0xffff0000, v226
	v_bfe_u32 v245, v227, 16, 1
	v_add3_u32 v227, v227, v245, s60
	v_and_b32_e32 v227, 0xffff0000, v227
	v_bfe_u32 v244, v228, 16, 1
	v_add3_u32 v228, v228, v244, s60
	v_and_b32_e32 v228, 0xffff0000, v228
	v_bfe_u32 v245, v229, 16, 1
	v_add3_u32 v229, v229, v245, s60
	v_and_b32_e32 v229, 0xffff0000, v229
	v_bfe_u32 v244, v230, 16, 1
	v_add3_u32 v230, v230, v244, s60
	v_and_b32_e32 v230, 0xffff0000, v230
	v_bfe_u32 v245, v231, 16, 1
	v_add3_u32 v231, v231, v245, s60
	v_and_b32_e32 v231, 0xffff0000, v231
	v_bfe_u32 v244, v232, 16, 1
	v_add3_u32 v232, v232, v244, s60
	v_and_b32_e32 v232, 0xffff0000, v232
	v_bfe_u32 v245, v233, 16, 1
	v_add3_u32 v233, v233, v245, s60
	v_and_b32_e32 v233, 0xffff0000, v233
	v_bfe_u32 v244, v234, 16, 1
	v_add3_u32 v234, v234, v244, s60
	v_and_b32_e32 v234, 0xffff0000, v234
	v_bfe_u32 v245, v235, 16, 1
	v_add3_u32 v235, v235, v245, s60
	v_and_b32_e32 v235, 0xffff0000, v235
	v_bfe_u32 v244, v236, 16, 1
	v_add3_u32 v236, v236, v244, s60
	v_and_b32_e32 v236, 0xffff0000, v236
	v_bfe_u32 v245, v237, 16, 1
	v_add3_u32 v237, v237, v245, s60
	v_and_b32_e32 v237, 0xffff0000, v237
	v_bfe_u32 v244, v238, 16, 1
	v_add3_u32 v238, v238, v244, s60
	v_and_b32_e32 v238, 0xffff0000, v238
	v_bfe_u32 v245, v239, 16, 1
	v_add3_u32 v239, v239, v245, s60
	v_and_b32_e32 v239, 0xffff0000, v239
	v_bfe_u32 v244, v240, 16, 1
	v_add3_u32 v240, v240, v244, s60
	v_and_b32_e32 v240, 0xffff0000, v240
	v_bfe_u32 v245, v241, 16, 1
	v_add3_u32 v241, v241, v245, s60
	v_and_b32_e32 v241, 0xffff0000, v241
	v_bfe_u32 v244, v242, 16, 1
	v_add3_u32 v242, v242, v244, s60
	v_and_b32_e32 v242, 0xffff0000, v242
	v_bfe_u32 v245, v243, 16, 1
	v_add3_u32 v243, v243, v245, s60
	v_and_b32_e32 v243, 0xffff0000, v243
	s_mov_b64 exec, s[46:47]
	v_add_f32_e32 v2, v2, v180
	v_add_f32_e32 v2, v2, v181
	v_add_f32_e32 v2, v2, v182
	v_add_f32_e32 v2, v2, v183
	v_add_f32_e32 v2, v2, v184
	v_add_f32_e32 v2, v2, v185
	v_add_f32_e32 v2, v2, v186
	v_add_f32_e32 v2, v2, v187
	v_add_f32_e32 v2, v2, v188
	v_add_f32_e32 v2, v2, v189
	v_add_f32_e32 v2, v2, v190
	v_add_f32_e32 v2, v2, v191
	v_add_f32_e32 v2, v2, v192
	v_add_f32_e32 v2, v2, v193
	v_add_f32_e32 v2, v2, v194
	v_add_f32_e32 v2, v2, v195
	v_add_f32_e32 v2, v2, v196
	v_add_f32_e32 v2, v2, v197
	v_add_f32_e32 v2, v2, v198
	v_add_f32_e32 v2, v2, v199
	v_add_f32_e32 v2, v2, v200
	v_add_f32_e32 v2, v2, v201
	v_add_f32_e32 v2, v2, v202
	v_add_f32_e32 v2, v2, v203
	v_add_f32_e32 v2, v2, v204
	v_add_f32_e32 v2, v2, v205
	v_add_f32_e32 v2, v2, v206
	v_add_f32_e32 v2, v2, v207
	v_add_f32_e32 v2, v2, v208
	v_add_f32_e32 v2, v2, v209
	v_add_f32_e32 v2, v2, v210
	v_add_f32_e32 v2, v2, v211
	v_add_f32_e32 v2, v2, v212
	v_add_f32_e32 v2, v2, v213
	v_add_f32_e32 v2, v2, v214
	v_add_f32_e32 v2, v2, v215
	v_add_f32_e32 v2, v2, v216
	v_add_f32_e32 v2, v2, v217
	v_add_f32_e32 v2, v2, v218
	v_add_f32_e32 v2, v2, v219
	v_add_f32_e32 v2, v2, v220
	v_add_f32_e32 v2, v2, v221
	v_add_f32_e32 v2, v2, v222
	v_add_f32_e32 v2, v2, v223
	v_add_f32_e32 v2, v2, v224
	v_add_f32_e32 v2, v2, v225
	v_add_f32_e32 v2, v2, v226
	v_add_f32_e32 v2, v2, v227
	v_add_f32_e32 v2, v2, v228
	v_add_f32_e32 v2, v2, v229
	v_add_f32_e32 v2, v2, v230
	v_add_f32_e32 v2, v2, v231
	v_add_f32_e32 v2, v2, v232
	v_add_f32_e32 v2, v2, v233
	v_add_f32_e32 v2, v2, v234
	v_add_f32_e32 v2, v2, v235
	v_add_f32_e32 v2, v2, v236
	v_add_f32_e32 v2, v2, v237
	v_add_f32_e32 v2, v2, v238
	v_add_f32_e32 v2, v2, v239
	v_add_f32_e32 v2, v2, v240
	v_add_f32_e32 v2, v2, v241
	v_add_f32_e32 v2, v2, v242
	v_add_f32_e32 v2, v2, v243
	s_movk_i32 s4, 0x100
	s_mov_b32 s5, 0
	s_branch .LBB0_151

; __device__ __forceinline__ unsigned f2bf(float f) { unsigned u = __builtin_bit_cast(unsigned, f); return (u + 0x7fffu + ((u >> 16) & 1u)) >> 16; }
; __device__ __forceinline__ void transpose_item(const float* W, int K, int nblk, int ldn, bf16* WT, int mode, LAS float* scr, int item, int lane, const float* lg = nullptr, const float* lb = nullptr, float* pcs = nullptr, float* pcb = nullptr) {
;     ...
;     if (lg) { const int n = lane & 31; float acc = 0.f;
; #pragma unroll 8
;         for (int kk = 0; kk < 64; ++kk) { const float w = scr[kk * 33 + n]; const float gk = lg[k0 + kk], bk = lb[k0 + kk]; acc += (lane < 32) ? __uint_as_float(f2bf(w * gk) << 16) : w * bk; }
;         ((lane < 32) ? pcs : pcb)[(size_t)kb * PSTR + r0 + n] = acc; }
.LBB0_167:
	v_mov_b32_e32 v110, s5
	v_mov_b32_e32 v111, s48
	v_mov_b32_e32 v112, s49
	v_mov_b32_e32 v113, s50
	v_mov_b32_e32 v114, v54
	v_mov_b32_e32 v115, 0
	v_cndmask_b32_e64 v110, v110, v112, s[6:7]
	v_cndmask_b32_e64 v111, v111, v113, s[6:7]
	v_lshl_add_u64 v[110:111], v[110:111], 0, v[114:115]
	global_load_dwordx4 v[116:119], v[110:111], off
	global_load_dwordx4 v[120:123], v[110:111], off offset:16
	global_load_dwordx4 v[124:127], v[110:111], off offset:32
	global_load_dwordx4 v[128:131], v[110:111], off offset:48
	global_load_dwordx4 v[132:135], v[110:111], off offset:64
	global_load_dwordx4 v[136:139], v[110:111], off offset:80
	global_load_dwordx4 v[140:143], v[110:111], off offset:96
	global_load_dwordx4 v[144:147], v[110:111], off offset:112
	global_load_dwordx4 v[148:151], v[110:111], off offset:128
	global_load_dwordx4 v[152:155], v[110:111], off offset:144
	global_load_dwordx4 v[156:159], v[110:111], off offset:160
	global_load_dwordx4 v[160:163], v[110:111], off offset:176
	global_load_dwordx4 v[164:167], v[110:111], off offset:192
	global_load_dwordx4 v[168:171], v[110:111], off offset:208
	global_load_dwordx4 v[172:175], v[110:111], off offset:224
	global_load_dwordx4 v[176:179], v[110:111], off offset:240
	ds_read_b32 v180, v3
	ds_read_b32 v181, v3 offset:132
	ds_read_b32 v182, v3 offset:264
	ds_read_b32 v183, v3 offset:396
	ds_read_b32 v184, v3 offset:528
	ds_read_b32 v185, v3 offset:660
	ds_read_b32 v186, v3 offset:792
	ds_read_b32 v187, v3 offset:924
	ds_read_b32 v188, v3 offset:1056
	ds_read_b32 v189, v3 offset:1188
	ds_read_b32 v190, v3 offset:1320
	ds_read_b32 v191, v3 offset:1452
	ds_read_b32 v192, v3 offset:1584
	ds_read_b32 v193, v3 offset:1716
	ds_read_b32 v194, v3 offset:1848
	ds_read_b32 v195, v3 offset:1980
	ds_read_b32 v196, v3 offset:2112
	ds_read_b32 v197, v3 offset:2244
	ds_read_b32 v198, v3 offset:2376
	ds_read_b32 v199, v3 offset:2508
	ds_read_b32 v200, v3 offset:2640
	ds_read_b32 v201, v3 offset:2772
	ds_read_b32 v202, v3 offset:2904
	ds_read_b32 v203, v3 offset:3036
	ds_read_b32 v204, v3 offset:3168
	ds_read_b32 v205, v3 offset:3300
	ds_read_b32 v206, v3 offset:3432
	ds_read_b32 v207, v3 offset:3564
	ds_read_b32 v208, v3 offset:3696
	ds_read_b32 v209, v3 offset:3828
	ds_read_b32 v210, v3 offset:3960
	ds_read_b32 v211, v3 offset:4092
	ds_read_b32 v212, v3 offset:4224
	ds_read_b32 v213, v3 offset:4356
	ds_read_b32 v214, v3 offset:4488
	ds_read_b32 v215, v3 offset:4620
	ds_read_b32 v216, v3 offset:4752
	ds_read_b32 v217, v3 offset:4884
	ds_read_b32 v218, v3 offset:5016
	ds_read_b32 v219, v3 offset:5148
	ds_read_b32 v220, v3 offset:5280
	ds_read_b32 v221, v3 offset:5412
	ds_read_b32 v222, v3 offset:5544
	ds_read_b32 v223, v3 offset:5676
	ds_read_b32 v224, v3 offset:5808
	ds_read_b32 v225, v3 offset:5940
	ds_read_b32 v226, v3 offset:6072
	ds_read_b32 v227, v3 offset:6204
	ds_read_b32 v228, v3 offset:6336
	ds_read_b32 v229, v3 offset:6468
	ds_read_b32 v230, v3 offset:6600
	ds_read_b32 v231, v3 offset:6732
	ds_read_b32 v232, v3 offset:6864
	ds_read_b32 v233, v3 offset:6996
	ds_read_b32 v234, v3 offset:7128
	ds_read_b32 v235, v3 offset:7260
	ds_read_b32 v236, v3 offset:7392
	ds_read_b32 v237, v3 offset:7524
	ds_read_b32 v238, v3 offset:7656
	ds_read_b32 v239, v3 offset:7788
	ds_read_b32 v240, v3 offset:7920
	ds_read_b32 v241, v3 offset:8052
	ds_read_b32 v242, v3 offset:8184
	ds_read_b32 v243, v3 offset:8316
	s_waitcnt vmcnt(0) lgkmcnt(0)
	v_mul_f32_e32 v180, v180, v116
	v_mul_f32_e32 v181, v181, v117
	v_mul_f32_e32 v182, v182, v118
	v_mul_f32_e32 v183, v183, v119
	v_mul_f32_e32 v184, v184, v120
	v_mul_f32_e32 v185, v185, v121
	v_mul_f32_e32 v186, v186, v122
	v_mul_f32_e32 v187, v187, v123
	v_mul_f32_e32 v188, v188, v124
	v_mul_f32_e32 v189, v189, v125
	v_mul_f32_e32 v190, v190, v126
	v_mul_f32_e32 v191, v191, v127
	v_mul_f32_e32 v192, v192, v128
	v_mul_f32_e32 v193, v193, v129
	v_mul_f32_e32 v194, v194, v130
	v_mul_f32_e32 v195, v195, v131
	v_mul_f32_e32 v196, v196, v132
	v_mul_f32_e32 v197, v197, v133
	v_mul_f32_e32 v198, v198, v134
	v_mul_f32_e32 v199, v199, v135
	v_mul_f32_e32 v200, v200, v136
	v_mul_f32_e32 v201, v201, v137
	v_mul_f32_e32 v202, v202, v138
	v_mul_f32_e32 v203, v203, v139
	v_mul_f32_e32 v204, v204, v140
	v_mul_f32_e32 v205, v205, v141
	v_mul_f32_e32 v206, v206, v142
	v_mul_f32_e32 v207, v207, v143
	v_mul_f32_e32 v208, v208, v144
	v_mul_f32_e32 v209, v209, v145
	v_mul_f32_e32 v210, v210, v146
	v_mul_f32_e32 v211, v211, v147
	v_mul_f32_e32 v212, v212, v148
	v_mul_f32_e32 v213, v213, v149
	v_mul_f32_e32 v214, v214, v150
	v_mul_f32_e32 v215, v215, v151
	v_mul_f32_e32 v216, v216, v152
	v_mul_f32_e32 v217, v217, v153
	v_mul_f32_e32 v218, v218, v154
	v_mul_f32_e32 v219, v219, v155
	v_mul_f32_e32 v220, v220, v156
	v_mul_f32_e32 v221, v221, v157
	v_mul_f32_e32 v222, v222, v158
	v_mul_f32_e32 v223, v223, v159
	v_mul_f32_e32 v224, v224, v160
	v_mul_f32_e32 v225, v225, v161
	v_mul_f32_e32 v226, v226, v162
	v_mul_f32_e32 v227, v227, v163
	v_mul_f32_e32 v228, v228, v164
	v_mul_f32_e32 v229, v229, v165
	v_mul_f32_e32 v230, v230, v166
	v_mul_f32_e32 v231, v231, v167
	v_mul_f32_e32 v232, v232, v168
	v_mul_f32_e32 v233, v233, v169
	v_mul_f32_e32 v234, v234, v170
	v_mul_f32_e32 v235, v235, v171
	v_mul_f32_e32 v236, v236, v172
	v_mul_f32_e32 v237, v237, v173
	v_mul_f32_e32 v238, v238, v174
	v_mul_f32_e32 v239, v239, v175
	v_mul_f32_e32 v240, v240, v176
	v_mul_f32_e32 v241, v241, v177
	v_mul_f32_e32 v242, v242, v178
	v_mul_f32_e32 v243, v243, v179
	s_mov_b64 s[46:47], exec
	s_andn2_b64 exec, exec, s[6:7]
	v_bfe_u32 v244, v180, 16, 1
	v_add3_u32 v180, v180, v244, s60
	v_and_b32_e32 v180, 0xffff0000, v180
; __device__ __forceinline__ unsigned f2bf(float f) { unsigned u = __builtin_bit_cast(unsigned, f); return (u + 0x7fffu + ((u >> 16) & 1u)) >> 16; }
; __device__ __forceinline__ void transpose_item(const float* W, int K, int nblk, int ldn, bf16* WT, int mode, LAS float* scr, int item, int lane, const float* lg = nullptr, const float* lb = nullptr, float* pcs = nullptr, float* pcb = nullptr) {
;     ...
;         for (int kk = 0; kk < 64; ++kk) { const float w = scr[kk * 33 + n]; const float gk = lg[k0 + kk], bk = lb[k0 + kk]; acc += (lane < 32) ? __uint_as_float(f2bf(w * gk) << 16) : w * bk; }
	v_bfe_u32 v245, v181, 16, 1
	v_add3_u32 v181, v181, v245, s60
	v_and_b32_e32 v181, 0xffff0000, v181
	v_bfe_u32 v244, v182, 16, 1
	v_add3_u32 v182, v182, v244, s60
	v_and_b32_e32 v182, 0xffff0000, v182
	v_bfe_u32 v245, v183, 16, 1
	v_add3_u32 v183, v183, v245, s60
	v_and_b32_e32 v183, 0xffff0000, v183
	v_bfe_u32 v244, v184, 16, 1
	v_add3_u32 v184, v184, v244, s60
	v_and_b32_e32 v184, 0xffff0000, v184
	v_bfe_u32 v245, v185, 16, 1
	v_add3_u32 v185, v185, v245, s60
	v_and_b32_e32 v185, 0xffff0000, v185
	v_bfe_u32 v244, v186, 16, 1
	v_add3_u32 v186, v186, v244, s60
	v_and_b32_e32 v186, 0xffff0000, v186
	v_bfe_u32 v245, v187, 16, 1
	v_add3_u32 v187, v187, v245, s60
	v_and_b32_e32 v187, 0xffff0000, v187
	v_bfe_u32 v244, v188, 16, 1
	v_add3_u32 v188, v188, v244, s60
	v_and_b32_e32 v188, 0xffff0000, v188
	v_bfe_u32 v245, v189, 16, 1
	v_add3_u32 v189, v189, v245, s60
	v_and_b32_e32 v189, 0xffff0000, v189
	v_bfe_u32 v244, v190, 16, 1
	v_add3_u32 v190, v190, v244, s60
	v_and_b32_e32 v190, 0xffff0000, v190
	v_bfe_u32 v245, v191, 16, 1
	v_add3_u32 v191, v191, v245, s60
	v_and_b32_e32 v191, 0xffff0000, v191
	v_bfe_u32 v244, v192, 16, 1
	v_add3_u32 v192, v192, v244, s60
	v_and_b32_e32 v192, 0xffff0000, v192
	v_bfe_u32 v245, v193, 16, 1
	v_add3_u32 v193, v193, v245, s60
	v_and_b32_e32 v193, 0xffff0000, v193
	v_bfe_u32 v244, v194, 16, 1
	v_add3_u32 v194, v194, v244, s60
	v_and_b32_e32 v194, 0xffff0000, v194
	v_bfe_u32 v245, v195, 16, 1
	v_add3_u32 v195, v195, v245, s60
	v_and_b32_e32 v195, 0xffff0000, v195
	v_bfe_u32 v244, v196, 16, 1
	v_add3_u32 v196, v196, v244, s60
	v_and_b32_e32 v196, 0xffff0000, v196
	v_bfe_u32 v245, v197, 16, 1
	v_add3_u32 v197, v197, v245, s60
	v_and_b32_e32 v197, 0xffff0000, v197
	v_bfe_u32 v244, v198, 16, 1
	v_add3_u32 v198, v198, v244, s60
	v_and_b32_e32 v198, 0xffff0000, v198
	v_bfe_u32 v245, v199, 16, 1
	v_add3_u32 v199, v199, v245, s60
	v_and_b32_e32 v199, 0xffff0000, v199
	v_bfe_u32 v244, v200, 16, 1
	v_add3_u32 v200, v200, v244, s60
	v_and_b32_e32 v200, 0xffff0000, v200
	v_bfe_u32 v245, v201, 16, 1
	v_add3_u32 v201, v201, v245, s60
	v_and_b32_e32 v201, 0xffff0000, v201
	v_bfe_u32 v244, v202, 16, 1
	v_add3_u32 v202, v202, v244, s60
	v_and_b32_e32 v202, 0xffff0000, v202
	v_bfe_u32 v245, v203, 16, 1
	v_add3_u32 v203, v203, v245, s60
	v_and_b32_e32 v203, 0xffff0000, v203
	v_bfe_u32 v244, v204, 16, 1
	v_add3_u32 v204, v204, v244, s60
	v_and_b32_e32 v204, 0xffff0000, v204
	v_bfe_u32 v245, v205, 16, 1
	v_add3_u32 v205, v205, v245, s60
	v_and_b32_e32 v205, 0xffff0000, v205
	v_bfe_u32 v244, v206, 16, 1
	v_add3_u32 v206, v206, v244, s60
	v_and_b32_e32 v206, 0xffff0000, v206
	v_bfe_u32 v245, v207, 16, 1
	v_add3_u32 v207, v207, v245, s60
	v_and_b32_e32 v207, 0xffff0000, v207
	v_bfe_u32 v244, v208, 16, 1
	v_add3_u32 v208, v208, v244, s60
	v_and_b32_e32 v208, 0xffff0000, v208
	v_bfe_u32 v245, v209, 16, 1
	v_add3_u32 v209, v209, v245, s60
	v_and_b32_e32 v209, 0xffff0000, v209
	v_bfe_u32 v244, v210, 16, 1
	v_add3_u32 v210, v210, v244, s60
	v_and_b32_e32 v210, 0xffff0000, v210
	v_bfe_u32 v245, v211, 16, 1
	v_add3_u32 v211, v211, v245, s60
	v_and_b32_e32 v211, 0xffff0000, v211
	v_bfe_u32 v244, v212, 16, 1
	v_add3_u32 v212, v212, v244, s60
	v_and_b32_e32 v212, 0xffff0000, v212
	v_bfe_u32 v245, v213, 16, 1
	v_add3_u32 v213, v213, v245, s60
	v_and_b32_e32 v213, 0xffff0000, v213
	v_bfe_u32 v244, v214, 16, 1
	v_add3_u32 v214, v214, v244, s60
	v_and_b32_e32 v214, 0xffff0000, v214
	v_bfe_u32 v245, v215, 16, 1
	v_add3_u32 v215, v215, v245, s60
	v_and_b32_e32 v215, 0xffff0000, v215
	v_bfe_u32 v244, v216, 16, 1
	v_add3_u32 v216, v216, v244, s60
	v_and_b32_e32 v216, 0xffff0000, v216
	v_bfe_u32 v245, v217, 16, 1
	v_add3_u32 v217, v217, v245, s60
	v_and_b32_e32 v217, 0xffff0000, v217
	v_bfe_u32 v244, v218, 16, 1
	v_add3_u32 v218, v218, v244, s60
	v_and_b32_e32 v218, 0xffff0000, v218
	v_bfe_u32 v245, v219, 16, 1
	v_add3_u32 v219, v219, v245, s60
	v_and_b32_e32 v219, 0xffff0000, v219
	v_bfe_u32 v244, v220, 16, 1
	v_add3_u32 v220, v220, v244, s60
	v_and_b32_e32 v220, 0xffff0000, v220
	v_bfe_u32 v245, v221, 16, 1
	v_add3_u32 v221, v221, v245, s60
; __device__ __forceinline__ unsigned f2bf(float f) { unsigned u = __builtin_bit_cast(unsigned, f); return (u + 0x7fffu + ((u >> 16) & 1u)) >> 16; }
; __device__ __forceinline__ void transpose_item(const float* W, int K, int nblk, int ldn, bf16* WT, int mode, LAS float* scr, int item, int lane, const float* lg = nullptr, const float* lb = nullptr, float* pcs = nullptr, float* pcb = nullptr) {
;     ...
;         for (int kk = 0; kk < 64; ++kk) { const float w = scr[kk * 33 + n]; const float gk = lg[k0 + kk], bk = lb[k0 + kk]; acc += (lane < 32) ? __uint_as_float(f2bf(w * gk) << 16) : w * bk; }
;         ((lane < 32) ? pcs : pcb)[(size_t)kb * PSTR + r0 + n] = acc; }
	v_and_b32_e32 v221, 0xffff0000, v221
	v_bfe_u32 v244, v222, 16, 1
	v_add3_u32 v222, v222, v244, s60
	v_and_b32_e32 v222, 0xffff0000, v222
	v_bfe_u32 v245, v223, 16, 1
	v_add3_u32 v223, v223, v245, s60
	v_and_b32_e32 v223, 0xffff0000, v223
	v_bfe_u32 v244, v224, 16, 1
	v_add3_u32 v224, v224, v244, s60
	v_and_b32_e32 v224, 0xffff0000, v224
	v_bfe_u32 v245, v225, 16, 1
	v_add3_u32 v225, v225, v245, s60
	v_and_b32_e32 v225, 0xffff0000, v225
	v_bfe_u32 v244, v226, 16, 1
	v_add3_u32 v226, v226, v244, s60
	v_and_b32_e32 v226, 0xffff0000, v226
	v_bfe_u32 v245, v227, 16, 1
	v_add3_u32 v227, v227, v245, s60
	v_and_b32_e32 v227, 0xffff0000, v227
	v_bfe_u32 v244, v228, 16, 1
	v_add3_u32 v228, v228, v244, s60
	v_and_b32_e32 v228, 0xffff0000, v228
	v_bfe_u32 v245, v229, 16, 1
	v_add3_u32 v229, v229, v245, s60
	v_and_b32_e32 v229, 0xffff0000, v229
	v_bfe_u32 v244, v230, 16, 1
	v_add3_u32 v230, v230, v244, s60
	v_and_b32_e32 v230, 0xffff0000, v230
	v_bfe_u32 v245, v231, 16, 1
	v_add3_u32 v231, v231, v245, s60
	v_and_b32_e32 v231, 0xffff0000, v231
	v_bfe_u32 v244, v232, 16, 1
	v_add3_u32 v232, v232, v244, s60
	v_and_b32_e32 v232, 0xffff0000, v232
	v_bfe_u32 v245, v233, 16, 1
	v_add3_u32 v233, v233, v245, s60
	v_and_b32_e32 v233, 0xffff0000, v233
	v_bfe_u32 v244, v234, 16, 1
	v_add3_u32 v234, v234, v244, s60
	v_and_b32_e32 v234, 0xffff0000, v234
	v_bfe_u32 v245, v235, 16, 1
	v_add3_u32 v235, v235, v245, s60
	v_and_b32_e32 v235, 0xffff0000, v235
	v_bfe_u32 v244, v236, 16, 1
	v_add3_u32 v236, v236, v244, s60
	v_and_b32_e32 v236, 0xffff0000, v236
	v_bfe_u32 v245, v237, 16, 1
	v_add3_u32 v237, v237, v245, s60
	v_and_b32_e32 v237, 0xffff0000, v237
	v_bfe_u32 v244, v238, 16, 1
	v_add3_u32 v238, v238, v244, s60
	v_and_b32_e32 v238, 0xffff0000, v238
	v_bfe_u32 v245, v239, 16, 1
	v_add3_u32 v239, v239, v245, s60
	v_and_b32_e32 v239, 0xffff0000, v239
	v_bfe_u32 v244, v240, 16, 1
	v_add3_u32 v240, v240, v244, s60
	v_and_b32_e32 v240, 0xffff0000, v240
	v_bfe_u32 v245, v241, 16, 1
	v_add3_u32 v241, v241, v245, s60
	v_and_b32_e32 v241, 0xffff0000, v241
	v_bfe_u32 v244, v242, 16, 1
	v_add3_u32 v242, v242, v244, s60
	v_and_b32_e32 v242, 0xffff0000, v242
	v_bfe_u32 v245, v243, 16, 1
	v_add3_u32 v243, v243, v245, s60
	v_and_b32_e32 v243, 0xffff0000, v243
	s_mov_b64 exec, s[46:47]
	v_add_f32_e32 v2, v2, v180
	v_add_f32_e32 v2, v2, v181
	v_add_f32_e32 v2, v2, v182
	v_add_f32_e32 v2, v2, v183
	v_add_f32_e32 v2, v2, v184
	v_add_f32_e32 v2, v2, v185
	v_add_f32_e32 v2, v2, v186
	v_add_f32_e32 v2, v2, v187
	v_add_f32_e32 v2, v2, v188
	v_add_f32_e32 v2, v2, v189
	v_add_f32_e32 v2, v2, v190
	v_add_f32_e32 v2, v2, v191
	v_add_f32_e32 v2, v2, v192
	v_add_f32_e32 v2, v2, v193
	v_add_f32_e32 v2, v2, v194
	v_add_f32_e32 v2, v2, v195
	v_add_f32_e32 v2, v2, v196
	v_add_f32_e32 v2, v2, v197
	v_add_f32_e32 v2, v2, v198
	v_add_f32_e32 v2, v2, v199
	v_add_f32_e32 v2, v2, v200
	v_add_f32_e32 v2, v2, v201
	v_add_f32_e32 v2, v2, v202
	v_add_f32_e32 v2, v2, v203
	v_add_f32_e32 v2, v2, v204
	v_add_f32_e32 v2, v2, v205
	v_add_f32_e32 v2, v2, v206
	v_add_f32_e32 v2, v2, v207
	v_add_f32_e32 v2, v2, v208
	v_add_f32_e32 v2, v2, v209
	v_add_f32_e32 v2, v2, v210
	v_add_f32_e32 v2, v2, v211
	v_add_f32_e32 v2, v2, v212
	v_add_f32_e32 v2, v2, v213
	v_add_f32_e32 v2, v2, v214
	v_add_f32_e32 v2, v2, v215
	v_add_f32_e32 v2, v2, v216
	v_add_f32_e32 v2, v2, v217
	v_add_f32_e32 v2, v2, v218
	v_add_f32_e32 v2, v2, v219
	v_add_f32_e32 v2, v2, v220
	v_add_f32_e32 v2, v2, v221
	v_add_f32_e32 v2, v2, v222
	v_add_f32_e32 v2, v2, v223
	v_add_f32_e32 v2, v2, v224
	v_add_f32_e32 v2, v2, v225
	v_add_f32_e32 v2, v2, v226
	v_add_f32_e32 v2, v2, v227
	v_add_f32_e32 v2, v2, v228
	v_add_f32_e32 v2, v2, v229
	v_add_f32_e32 v2, v2, v230
	v_add_f32_e32 v2, v2, v231
	v_add_f32_e32 v2, v2, v232
	v_add_f32_e32 v2, v2, v233
	v_add_f32_e32 v2, v2, v234
	v_add_f32_e32 v2, v2, v235
	v_add_f32_e32 v2, v2, v236
	v_add_f32_e32 v2, v2, v237
	v_add_f32_e32 v2, v2, v238
	v_add_f32_e32 v2, v2, v239
	v_add_f32_e32 v2, v2, v240
	v_add_f32_e32 v2, v2, v241
	v_add_f32_e32 v2, v2, v242
	v_add_f32_e32 v2, v2, v243
	s_movk_i32 s44, 0x100
	s_mov_b32 s45, 0
	s_branch .LBB0_5
